# speedup vs baseline: 1.0006x; 1.0006x over previous
; __global__ void __launch_bounds__(512) fwd_megakernel(Args args) {
;     ...
;             float ga = 0.f, gk = 0.f, gb = 0.f, gl = 0.f, sk = 0.f, rb = 0.f;
;             for (int j = 0; j < 64; ++j) { ga = fmaxf(ga, fabsf(args.in[6][j])); gk = fmaxf(gk, fabsf(args.in[7][j])); gb = fmaxf(gb, fabsf(args.in[9][j])); gl = fmaxf(gl, fabsf(args.in[10][j])); }
;             for (int j = 0; j < 8; ++j) sk = fmaxf(sk, fabsf(args.in[8][j]));
;             for (int e = lane; e < 8 * 465; e += 64) rb = fmaxf(rb, fabsf(args.in[11][e]));
; #pragma unroll
;             for (int o = 1; o < 64; o <<= 1) rb = fmaxf(rb, __shfl_xor(rb, o));
.LBB0_362:
	s_or_b64 exec, exec, s[0:1]
	s_mov_b64 s[0:1], 0
	s_waitcnt lgkmcnt(0)
	v_mov_b32_e32 v0, 0
	v_mov_b32_e32 v12, 0
	v_mov_b32_e32 v15, 0
	v_mov_b32_e32 v14, 0
	v_mov_b32_e32 v13, 0
	s_barrier
	v_lshrrev_b32_e32 v1, 8, v206
	s_nop 1
	v_readfirstlane_b32 s98, v1
	s_nop 3
	s_cmp_eq_u32 s98, 0
	s_cbranch_scc1 .Lp2_noprio
	s_setprio 1
